# phase top: the three kernel-argument scalar loads issued together, one wait
# baseline (speedup 1.0000x reference)
.LBB0_21:
	s_load_dwordx16 s[4:19], s[22:23], 0x0
	s_load_dwordx16 s[56:71], s[22:23], 0x40
	s_load_dword s100, s[22:23], 0x90
	s_add_u32 s80, s0, 0x2980000
	s_addc_u32 s81, s1, 0
	s_add_u32 s78, s0, 0x80000
	s_addc_u32 s79, s1, 0
	s_waitcnt lgkmcnt(0)
	v_writelane_b32 v254, s4, 14
	s_cmp_lg_u32 s74, 0
	s_cselect_b64 s[24:25], -1, 0
	v_writelane_b32 v254, s5, 15
	v_writelane_b32 v254, s6, 16
	v_writelane_b32 v254, s7, 17
	v_writelane_b32 v254, s8, 18
	v_writelane_b32 v254, s9, 19
	v_writelane_b32 v254, s10, 20
	v_writelane_b32 v254, s11, 21
	v_writelane_b32 v254, s12, 22
	v_writelane_b32 v254, s13, 23
	v_writelane_b32 v254, s14, 24
	v_writelane_b32 v254, s15, 25
	v_writelane_b32 v254, s16, 26
	v_writelane_b32 v254, s17, 27
	v_writelane_b32 v254, s18, 28
	v_writelane_b32 v254, s19, 29
	s_mov_b64 s[4:5], s[56:57]
	s_mov_b64 s[6:7], s[58:59]
	s_mov_b64 s[8:9], s[60:61]
	s_mov_b64 s[10:11], s[62:63]
	s_mov_b64 s[12:13], s[64:65]
	s_mov_b64 s[14:15], s[66:67]
	s_mov_b64 s[16:17], s[68:69]
	s_mov_b64 s[18:19], s[70:71]
	v_and_b32_e32 v218, 63, v233
	s_and_b64 vcc, exec, s[24:25]
	s_waitcnt lgkmcnt(0)
	v_writelane_b32 v254, s4, 30
	s_nop 1
	v_writelane_b32 v254, s5, 31
	v_writelane_b32 v254, s6, 32
	v_writelane_b32 v254, s7, 33
	v_writelane_b32 v254, s8, 34
	v_writelane_b32 v254, s9, 35
	v_writelane_b32 v254, s10, 36
	v_writelane_b32 v254, s11, 37
	v_writelane_b32 v254, s12, 38
	v_writelane_b32 v254, s13, 39
	v_writelane_b32 v254, s14, 40
	v_writelane_b32 v254, s15, 41
	v_writelane_b32 v254, s16, 42
	v_writelane_b32 v254, s17, 43
	v_writelane_b32 v254, s18, 44
	v_writelane_b32 v254, s19, 45
	s_cbranch_vccz .LBB0_27
	v_writelane_b32 v254, s21, 46
	v_writelane_b32 v254, s52, 47
	s_add_u32 s90, s0, 0x6200000
	s_addc_u32 s91, s1, 0
	v_writelane_b32 v254, s53, 48
	v_writelane_b32 v254, s22, 49
	s_add_u32 s82, s0, 0xa200000
	s_addc_u32 s83, s1, 0
	s_add_u32 s84, s0, 0xc200000
	v_writelane_b32 v254, s23, 50
	s_addc_u32 s85, s1, 0
	s_waitcnt lgkmcnt(0)
	v_writelane_b32 v254, s100, 51
	s_mov_b64 s[8:9], -1
	s_mov_b64 s[4:5], 0
	s_cmp_lt_i32 s74, 2
	s_mov_b64 s[6:7], 0
	s_cbranch_scc1 .LBB0_83
	s_cmp_eq_u32 s74, 2
	s_mov_b64 s[6:7], -1
	s_cbranch_scc0 .LBB0_82
	s_cmpk_lg_i32 s98, 0x100
	s_mov_b64 s[6:7], 0
	s_cbranch_scc1 .LBB0_28
	v_readlane_b32 s6, v254, 49
	v_readlane_b32 s7, v254, 50
	s_load_dword s6, s[6:7], 0x88
	s_waitcnt lgkmcnt(0)
	s_cmp_lt_i32 s6, 2
	s_cselect_b64 s[6:7], -1, 0
	s_andn2_b64 vcc, exec, s[6:7]
	s_cbranch_vccz .LBB0_29

.LBB0_287:
	s_ashr_i32 s21, s20, 31
	s_lshl_b64 s[22:23], s[20:21], 19
	s_add_u32 s22, s80, s22
	s_addc_u32 s23, s81, s23
	s_and_b64 s[24:25], s[6:7], exec
	s_cselect_b32 s21, s23, s29
	s_cselect_b32 s36, s22, s28
	s_ashr_i32 s19, s18, 31
	s_lshl_b64 s[24:25], s[18:19], 19
	s_add_u32 s24, s40, s24
	s_addc_u32 s25, s41, s25
	s_and_b64 s[34:35], s[6:7], exec
	s_cselect_b32 s19, s25, s31
	s_cselect_b32 s37, s24, s30
	s_add_u32 s38, s30, 0x100
	s_addc_u32 s39, s31, 0
	s_add_u32 s28, s28, 0x40080
	s_addc_u32 s29, s29, 0
	s_mov_b32 s55, -2
	s_add_u32 s30, s28, 0xfffc0080
	s_addc_u32 s31, s29, -1
	s_add_i32 s56, 0, 0x10000
	s_cmp_eq_u32 s55, 12
	s_cselect_b32 s35, s21, s31
	s_cselect_b32 s34, s36, s30
	s_cselect_b32 s31, s19, s39
	s_cselect_b32 s30, s37, s38
	s_add_i32 s58, 0, 0x14000
	v_add_u32_e32 v166, s56, v147
	v_add_u32_e32 v182, s58, v147
	ds_read_b128 v[142:145], v166
	ds_read_b128 v[158:161], v166 offset:1024
	ds_read_b128 v[162:165], v166 offset:2048
	ds_read_b128 v[166:169], v166 offset:3072
	ds_read_b128 v[170:173], v182
	ds_read_b128 v[174:177], v182 offset:1024
	ds_read_b128 v[178:181], v182 offset:2048
	ds_read_b128 v[182:185], v182 offset:3072
	v_lshl_add_u64 v[224:225], s[28:29], 0, v[140:141]
	s_add_i32 m0, s44, 0xc000
	ds_read_b128 v[186:189], v157
	ds_read_b128 v[190:193], v157 offset:1024
	ds_read_b128 v[194:197], v157 offset:2048
	ds_read_b128 v[198:201], v157 offset:3072
	ds_read_b128 v[202:205], v157 offset:4096
	ds_read_b128 v[206:209], v157 offset:5120
	ds_read_b128 v[220:223], v157 offset:6144
	ds_read_b128 v[236:239], v157 offset:7168
	global_load_lds_dwordx4 v[224:225], off
	v_lshl_add_u64 v[224:225], s[28:29], 0, v[138:139]
	s_add_i32 m0, s44, 0xe000
	s_nop 0
	global_load_lds_dwordx4 v[224:225], off
	s_nop 0
	s_nop 0
	s_nop 0
	s_nop 0
	s_nop 0
	s_nop 0
	s_nop 0
	s_nop 0
	s_nop 0
	s_nop 0
	s_nop 0
	s_waitcnt vmcnt(8)
	s_waitcnt lgkmcnt(0)
	s_barrier
	s_waitcnt lgkmcnt(0)
	v_mfma_f32_16x16x32_bf16 v[126:129], v[142:145], v[186:189], 0
	v_mfma_f32_16x16x32_bf16 v[122:125], v[162:165], v[186:189], 0
	v_mfma_f32_16x16x32_bf16 v[110:113], v[142:145], v[194:197], 0
	v_mfma_f32_16x16x32_bf16 v[106:109], v[162:165], v[194:197], 0
	v_mfma_f32_16x16x32_bf16 v[94:97], v[142:145], v[202:205], 0
	v_mfma_f32_16x16x32_bf16 v[90:93], v[162:165], v[202:205], 0
	v_mfma_f32_16x16x32_bf16 v[78:81], v[142:145], v[220:223], 0
	v_mfma_f32_16x16x32_bf16 v[74:77], v[162:165], v[220:223], 0
	v_mfma_f32_16x16x32_bf16 v[126:129], v[158:161], v[190:193], v[126:129]
	v_mfma_f32_16x16x32_bf16 v[122:125], v[166:169], v[190:193], v[122:125]
	v_mfma_f32_16x16x32_bf16 v[110:113], v[158:161], v[198:201], v[110:113]
	v_mfma_f32_16x16x32_bf16 v[106:109], v[166:169], v[198:201], v[106:109]
	v_mfma_f32_16x16x32_bf16 v[94:97], v[158:161], v[206:209], v[94:97]
	v_mfma_f32_16x16x32_bf16 v[90:93], v[166:169], v[206:209], v[90:93]
	v_mfma_f32_16x16x32_bf16 v[78:81], v[158:161], v[236:239], v[78:81]
	v_mfma_f32_16x16x32_bf16 v[74:77], v[166:169], v[236:239], v[74:77]
	v_mfma_f32_16x16x32_bf16 v[118:121], v[170:173], v[186:189], 0
	v_mfma_f32_16x16x32_bf16 v[114:117], v[178:181], v[186:189], 0
	v_mfma_f32_16x16x32_bf16 v[102:105], v[170:173], v[194:197], 0
	v_mfma_f32_16x16x32_bf16 v[98:101], v[178:181], v[194:197], 0
	v_mfma_f32_16x16x32_bf16 v[86:89], v[170:173], v[202:205], 0
	v_mfma_f32_16x16x32_bf16 v[82:85], v[178:181], v[202:205], 0
	v_mfma_f32_16x16x32_bf16 v[70:73], v[170:173], v[220:223], 0
	v_mfma_f32_16x16x32_bf16 v[66:69], v[178:181], v[220:223], 0
	v_mfma_f32_16x16x32_bf16 v[118:121], v[174:177], v[190:193], v[118:121]
	v_mfma_f32_16x16x32_bf16 v[114:117], v[182:185], v[190:193], v[114:117]
	v_mfma_f32_16x16x32_bf16 v[102:105], v[174:177], v[198:201], v[102:105]
	v_mfma_f32_16x16x32_bf16 v[98:101], v[182:185], v[198:201], v[98:101]
	v_mfma_f32_16x16x32_bf16 v[86:89], v[174:177], v[206:209], v[86:89]
	v_mfma_f32_16x16x32_bf16 v[82:85], v[182:185], v[206:209], v[82:85]
	v_mfma_f32_16x16x32_bf16 v[70:73], v[174:177], v[236:239], v[70:73]
	v_mfma_f32_16x16x32_bf16 v[66:69], v[182:185], v[236:239], v[66:69]
	s_barrier
	s_add_i32 s56, s56, s27
	v_lshl_add_u64 v[224:225], s[30:31], 0, v[132:133]
	s_mov_b32 m0, s56
	ds_read_b128 v[186:189], v157 offset:16384
	ds_read_b128 v[190:193], v157 offset:17408
	ds_read_b128 v[194:197], v157 offset:18432
	ds_read_b128 v[198:201], v157 offset:19456
	ds_read_b128 v[202:205], v157 offset:20480
	ds_read_b128 v[206:209], v157 offset:21504
	ds_read_b128 v[220:223], v157 offset:22528
	ds_read_b128 v[236:239], v157 offset:23552
	global_load_lds_dwordx4 v[224:225], off
	s_add_i32 m0, s56, 0x2000
	s_add_u32 s56, s30, 0x40000
	v_lshl_add_u64 v[230:231], s[30:31], 0, v[136:137]
	s_addc_u32 s57, s31, 0
	s_add_i32 s58, s58, s27
	global_load_lds_dwordx4 v[230:231], off
	v_lshl_add_u64 v[240:241], s[56:57], 0, v[132:133]
	s_mov_b32 m0, s58
	v_lshl_add_u64 v[242:243], s[34:35], 0, v[134:135]
	global_load_lds_dwordx4 v[240:241], off
	v_lshl_add_u64 v[240:241], s[56:57], 0, v[136:137]
	s_add_i32 m0, s58, 0x2000
	s_nop 0
	global_load_lds_dwordx4 v[240:241], off
	v_lshl_add_u64 v[240:241], s[34:35], 0, v[130:131]
	s_mov_b32 m0, s44
	s_nop 0
	global_load_lds_dwordx4 v[240:241], off
	s_mov_b32 m0, s45
	s_nop 0
	global_load_lds_dwordx4 v[242:243], off
	s_nop 0
	s_nop 0
	s_nop 0
	s_waitcnt vmcnt(8)
	s_waitcnt lgkmcnt(0)
	s_barrier
	s_waitcnt lgkmcnt(0)
	v_mfma_f32_16x16x32_bf16 v[62:65], v[142:145], v[186:189], 0
	v_mfma_f32_16x16x32_bf16 v[58:61], v[162:165], v[186:189], 0
	v_mfma_f32_16x16x32_bf16 v[46:49], v[142:145], v[194:197], 0
	v_mfma_f32_16x16x32_bf16 v[42:45], v[162:165], v[194:197], 0
	v_mfma_f32_16x16x32_bf16 v[30:33], v[142:145], v[202:205], 0
	v_mfma_f32_16x16x32_bf16 v[26:29], v[162:165], v[202:205], 0
	v_mfma_f32_16x16x32_bf16 v[14:17], v[142:145], v[220:223], 0
	v_mfma_f32_16x16x32_bf16 v[10:13], v[162:165], v[220:223], 0
	v_mfma_f32_16x16x32_bf16 v[62:65], v[158:161], v[190:193], v[62:65]
	v_mfma_f32_16x16x32_bf16 v[58:61], v[166:169], v[190:193], v[58:61]
	v_mfma_f32_16x16x32_bf16 v[46:49], v[158:161], v[198:201], v[46:49]
	v_mfma_f32_16x16x32_bf16 v[42:45], v[166:169], v[198:201], v[42:45]
	v_mfma_f32_16x16x32_bf16 v[30:33], v[158:161], v[206:209], v[30:33]
	v_mfma_f32_16x16x32_bf16 v[26:29], v[166:169], v[206:209], v[26:29]
	v_mfma_f32_16x16x32_bf16 v[14:17], v[158:161], v[236:239], v[14:17]
	v_mfma_f32_16x16x32_bf16 v[10:13], v[166:169], v[236:239], v[10:13]
	v_mfma_f32_16x16x32_bf16 v[54:57], v[170:173], v[186:189], 0
	v_mfma_f32_16x16x32_bf16 v[50:53], v[178:181], v[186:189], 0
	v_mfma_f32_16x16x32_bf16 v[38:41], v[170:173], v[194:197], 0
	v_mfma_f32_16x16x32_bf16 v[34:37], v[178:181], v[194:197], 0
	v_mfma_f32_16x16x32_bf16 v[22:25], v[170:173], v[202:205], 0
	v_mfma_f32_16x16x32_bf16 v[18:21], v[178:181], v[202:205], 0
	v_mfma_f32_16x16x32_bf16 v[6:9], v[170:173], v[220:223], 0
	v_mfma_f32_16x16x32_bf16 v[2:5], v[178:181], v[220:223], 0
	v_mfma_f32_16x16x32_bf16 v[54:57], v[174:177], v[190:193], v[54:57]
	v_mfma_f32_16x16x32_bf16 v[50:53], v[182:185], v[190:193], v[50:53]
	v_mfma_f32_16x16x32_bf16 v[38:41], v[174:177], v[198:201], v[38:41]
	v_mfma_f32_16x16x32_bf16 v[34:37], v[182:185], v[198:201], v[34:37]
	v_mfma_f32_16x16x32_bf16 v[22:25], v[174:177], v[206:209], v[22:25]
	v_mfma_f32_16x16x32_bf16 v[18:21], v[182:185], v[206:209], v[18:21]
	v_mfma_f32_16x16x32_bf16 v[6:9], v[174:177], v[236:239], v[6:9]
	v_mfma_f32_16x16x32_bf16 v[2:5], v[182:185], v[236:239], v[2:5]
	s_barrier
	s_add_i32 s56, 0, 0x18000
	s_add_i32 s57, 0, 0x1c000
	v_add_u32_e32 v166, s56, v147
	v_add_u32_e32 v182, s57, v147
	ds_read_b128 v[142:145], v166
	ds_read_b128 v[158:161], v166 offset:1024
	ds_read_b128 v[162:165], v166 offset:2048
	ds_read_b128 v[166:169], v166 offset:3072
	ds_read_b128 v[170:173], v182
	ds_read_b128 v[174:177], v182 offset:1024
	ds_read_b128 v[178:181], v182 offset:2048
	ds_read_b128 v[182:185], v182 offset:3072
	s_add_u32 s34, s34, 0x40000
	s_addc_u32 s35, s35, 0
	s_mov_b32 m0, s43
	v_lshl_add_u64 v[244:245], s[34:35], 0, v[130:131]
	ds_read_b128 v[186:189], v157 offset:32768
	ds_read_b128 v[190:193], v157 offset:33792
	ds_read_b128 v[194:197], v157 offset:34816
	ds_read_b128 v[198:201], v157 offset:35840
	ds_read_b128 v[202:205], v157 offset:36864
	ds_read_b128 v[206:209], v157 offset:37888
	ds_read_b128 v[220:223], v157 offset:38912
	ds_read_b128 v[236:239], v157 offset:39936
	global_load_lds_dwordx4 v[244:245], off
	v_lshl_add_u64 v[244:245], s[34:35], 0, v[134:135]
	s_mov_b32 m0, s46
	s_nop 0
	global_load_lds_dwordx4 v[244:245], off
	s_nop 0
	s_nop 0
	s_nop 0
	s_nop 0
	s_nop 0
	s_nop 0
	s_nop 0
	s_waitcnt vmcnt(8)
	s_waitcnt lgkmcnt(0)
	s_barrier
	s_waitcnt lgkmcnt(0)
	v_mfma_f32_16x16x32_bf16 v[126:129], v[142:145], v[186:189], v[126:129]
	v_mfma_f32_16x16x32_bf16 v[122:125], v[162:165], v[186:189], v[122:125]
	v_mfma_f32_16x16x32_bf16 v[110:113], v[142:145], v[194:197], v[110:113]
	v_mfma_f32_16x16x32_bf16 v[106:109], v[162:165], v[194:197], v[106:109]
	v_mfma_f32_16x16x32_bf16 v[94:97], v[142:145], v[202:205], v[94:97]
	v_mfma_f32_16x16x32_bf16 v[90:93], v[162:165], v[202:205], v[90:93]
	v_mfma_f32_16x16x32_bf16 v[78:81], v[142:145], v[220:223], v[78:81]
	v_mfma_f32_16x16x32_bf16 v[74:77], v[162:165], v[220:223], v[74:77]
	v_mfma_f32_16x16x32_bf16 v[126:129], v[158:161], v[190:193], v[126:129]
	v_mfma_f32_16x16x32_bf16 v[122:125], v[166:169], v[190:193], v[122:125]
	v_mfma_f32_16x16x32_bf16 v[110:113], v[158:161], v[198:201], v[110:113]
	v_mfma_f32_16x16x32_bf16 v[106:109], v[166:169], v[198:201], v[106:109]
	v_mfma_f32_16x16x32_bf16 v[94:97], v[158:161], v[206:209], v[94:97]
	v_mfma_f32_16x16x32_bf16 v[90:93], v[166:169], v[206:209], v[90:93]
	v_mfma_f32_16x16x32_bf16 v[78:81], v[158:161], v[236:239], v[78:81]
	v_mfma_f32_16x16x32_bf16 v[74:77], v[166:169], v[236:239], v[74:77]
	v_mfma_f32_16x16x32_bf16 v[118:121], v[170:173], v[186:189], v[118:121]
	v_mfma_f32_16x16x32_bf16 v[114:117], v[178:181], v[186:189], v[114:117]
	v_mfma_f32_16x16x32_bf16 v[102:105], v[170:173], v[194:197], v[102:105]
	v_mfma_f32_16x16x32_bf16 v[98:101], v[178:181], v[194:197], v[98:101]
	v_mfma_f32_16x16x32_bf16 v[86:89], v[170:173], v[202:205], v[86:89]
	v_mfma_f32_16x16x32_bf16 v[82:85], v[178:181], v[202:205], v[82:85]
	v_mfma_f32_16x16x32_bf16 v[70:73], v[170:173], v[220:223], v[70:73]
	v_mfma_f32_16x16x32_bf16 v[66:69], v[178:181], v[220:223], v[66:69]
	v_mfma_f32_16x16x32_bf16 v[118:121], v[174:177], v[190:193], v[118:121]
	v_mfma_f32_16x16x32_bf16 v[114:117], v[182:185], v[190:193], v[114:117]
	v_mfma_f32_16x16x32_bf16 v[102:105], v[174:177], v[198:201], v[102:105]
	v_mfma_f32_16x16x32_bf16 v[98:101], v[182:185], v[198:201], v[98:101]
	v_mfma_f32_16x16x32_bf16 v[86:89], v[174:177], v[206:209], v[86:89]
	v_mfma_f32_16x16x32_bf16 v[82:85], v[182:185], v[206:209], v[82:85]
	v_mfma_f32_16x16x32_bf16 v[70:73], v[174:177], v[236:239], v[70:73]
	v_mfma_f32_16x16x32_bf16 v[66:69], v[182:185], v[236:239], v[66:69]
	s_barrier
	s_add_i32 s34, s56, s27
	v_lshl_add_u64 v[224:225], v[224:225], 0, s[96:97]
	s_mov_b32 m0, s34
	ds_read_b128 v[186:189], v157 offset:49152
	ds_read_b128 v[190:193], v157 offset:50176
	ds_read_b128 v[194:197], v157 offset:51200
	ds_read_b128 v[198:201], v157 offset:52224
	ds_read_b128 v[202:205], v157 offset:53248
	ds_read_b128 v[206:209], v157 offset:54272
	ds_read_b128 v[220:223], v157 offset:55296
	ds_read_b128 v[236:239], v157 offset:56320
	global_load_lds_dwordx4 v[224:225], off
	s_add_i32 m0, s34, 0x2000
	s_add_u32 s30, s30, 0x40080
	v_lshl_add_u64 v[224:225], v[230:231], 0, s[96:97]
	s_addc_u32 s31, s31, 0
	s_add_i32 s34, s57, s27
	global_load_lds_dwordx4 v[224:225], off
	v_lshl_add_u64 v[224:225], s[30:31], 0, v[132:133]
	s_mov_b32 m0, s34
	s_nop 0
	global_load_lds_dwordx4 v[224:225], off
	v_lshl_add_u64 v[224:225], s[30:31], 0, v[136:137]
	s_add_i32 m0, s34, 0x2000
	s_nop 0
	global_load_lds_dwordx4 v[224:225], off
	v_lshl_add_u64 v[224:225], v[240:241], 0, s[96:97]
	s_mov_b32 m0, s47
	s_nop 0
	global_load_lds_dwordx4 v[224:225], off
	v_lshl_add_u64 v[224:225], v[242:243], 0, s[96:97]
	s_mov_b32 m0, s48
	s_nop 0
	global_load_lds_dwordx4 v[224:225], off
	s_nop 0
	s_nop 0
	s_waitcnt vmcnt(8)
	s_waitcnt lgkmcnt(0)
	s_barrier
	s_waitcnt lgkmcnt(0)
	v_mfma_f32_16x16x32_bf16 v[62:65], v[142:145], v[186:189], v[62:65]
	v_mfma_f32_16x16x32_bf16 v[58:61], v[162:165], v[186:189], v[58:61]
	v_mfma_f32_16x16x32_bf16 v[46:49], v[142:145], v[194:197], v[46:49]
	v_mfma_f32_16x16x32_bf16 v[42:45], v[162:165], v[194:197], v[42:45]
	v_mfma_f32_16x16x32_bf16 v[30:33], v[142:145], v[202:205], v[30:33]
	v_mfma_f32_16x16x32_bf16 v[26:29], v[162:165], v[202:205], v[26:29]
	v_mfma_f32_16x16x32_bf16 v[14:17], v[142:145], v[220:223], v[14:17]
	v_mfma_f32_16x16x32_bf16 v[10:13], v[162:165], v[220:223], v[10:13]
	v_mfma_f32_16x16x32_bf16 v[62:65], v[158:161], v[190:193], v[62:65]
	v_mfma_f32_16x16x32_bf16 v[58:61], v[166:169], v[190:193], v[58:61]
	v_mfma_f32_16x16x32_bf16 v[46:49], v[158:161], v[198:201], v[46:49]
	v_mfma_f32_16x16x32_bf16 v[42:45], v[166:169], v[198:201], v[42:45]
	v_mfma_f32_16x16x32_bf16 v[30:33], v[158:161], v[206:209], v[30:33]
	v_mfma_f32_16x16x32_bf16 v[26:29], v[166:169], v[206:209], v[26:29]
	v_mfma_f32_16x16x32_bf16 v[14:17], v[158:161], v[236:239], v[14:17]
	v_mfma_f32_16x16x32_bf16 v[10:13], v[166:169], v[236:239], v[10:13]
	v_mfma_f32_16x16x32_bf16 v[54:57], v[170:173], v[186:189], v[54:57]
	v_mfma_f32_16x16x32_bf16 v[50:53], v[178:181], v[186:189], v[50:53]
	v_mfma_f32_16x16x32_bf16 v[38:41], v[170:173], v[194:197], v[38:41]
	v_mfma_f32_16x16x32_bf16 v[34:37], v[178:181], v[194:197], v[34:37]
	v_mfma_f32_16x16x32_bf16 v[22:25], v[170:173], v[202:205], v[22:25]
	v_mfma_f32_16x16x32_bf16 v[18:21], v[178:181], v[202:205], v[18:21]
	v_mfma_f32_16x16x32_bf16 v[6:9], v[170:173], v[220:223], v[6:9]
	v_mfma_f32_16x16x32_bf16 v[2:5], v[178:181], v[220:223], v[2:5]
	v_mfma_f32_16x16x32_bf16 v[54:57], v[174:177], v[190:193], v[54:57]
	v_mfma_f32_16x16x32_bf16 v[50:53], v[182:185], v[190:193], v[50:53]
	v_mfma_f32_16x16x32_bf16 v[38:41], v[174:177], v[198:201], v[38:41]
	v_mfma_f32_16x16x32_bf16 v[34:37], v[182:185], v[198:201], v[34:37]
	v_mfma_f32_16x16x32_bf16 v[22:25], v[174:177], v[206:209], v[22:25]
	v_mfma_f32_16x16x32_bf16 v[18:21], v[182:185], v[206:209], v[18:21]
	v_mfma_f32_16x16x32_bf16 v[6:9], v[174:177], v[236:239], v[6:9]
	v_mfma_f32_16x16x32_bf16 v[2:5], v[182:185], v[236:239], v[2:5]
	s_barrier
	s_add_i32 s55, s55, 2
	s_add_u32 s38, s38, 0x100
	s_addc_u32 s39, s39, 0
	s_add_u32 s28, s28, 0x100
	s_addc_u32 s29, s29, 0
	s_cmp_gt_u32 s55, 13
